# P2 diff finalize: MIX stores widened from 8 dwordx2 to 4 dwordx4 per wave via v_permlane16_swap row pairs (same bytes, same addresses)
# speedup vs baseline: 1.0126x; 1.0047x over previous
; template <bool DIFF>
; __device__ __forceinline__ void attn_item(LAS unsigned char* lds, const bf16_t* Z, bf16_t* MIX, int b, int h, int t, float lam, float shift, const float* gain, int tid, int wid, int lane) {
;     ...
;     float inv0 = 1.f, inv1 = 0.f;
;     if (DIFF) {
; #pragma unroll
;         for (int c = 0; c < NC; ++c) l[c] = quad_sum(l[c]);
;         inv0 = 1.0f / l[0]; inv1 = lam / l[NC - 1];
;     }
;     float ss = 0.f;
; #pragma unroll
;     for (int eb = 0; eb < 8; ++eb)
; #pragma unroll
;         for (int i = 0; i < 4; ++i) { float v = O[0][eb][i] * inv0; if (DIFF) v -= O[NC - 1][eb][i] * inv1; O[0][eb][i] = v; ss += v * v; }
;     ss = quad_sum(ss);
;     const float r = rsqrtf(ss * (1.0f / 128.0f) + EPS) * (DIFF ? 0.8f : 1.0f);
;     const int row = row0 + q16;
;     const bf16_t* gp = Z + (size_t)row * DIN + gcol + 4 * quad;
;     bf16_t* op = MIX + (size_t)row * DM + (DIFF ? 1024 : 0) + 128 * h + 4 * quad;
; #pragma unroll
;     for (int eb = 0; eb < 8; ++eb) {
;         const u32x2 gw = *(const u32x2*)(gp + 16 * eb);
;         const f32x4 gn = *(const f32x4*)(gain + 16 * eb + 4 * quad);
.Ldx_done:
.LBB0_574:
	s_waitcnt lgkmcnt(0)
	ds_swizzle_b32 v68, v131 offset:swizzle(SWAP,16)
	ds_swizzle_b32 v69, v130 offset:swizzle(SWAP,16)
	v_ashrrev_i32_e32 v129, 31, v128
	v_lshlrev_b64 v[80:81], 1, v[128:129]
	s_lshl_b32 s86, s80, 1
	s_waitcnt lgkmcnt(0)
	v_add_f32_e32 v68, v131, v68
	v_mov_b32_e32 v70, v68
	s_nop 1
	v_permlane32_swap_b32_e32 v68, v70
	v_add_f32_e32 v68, v68, v70
	v_div_scale_f32 v70, s[0:1], v68, v68, 1.0
	v_rcp_f32_e32 v72, v70
	v_add_f32_e32 v69, v130, v69
	v_mov_b32_e32 v71, v69
	s_nop 1
	v_permlane32_swap_b32_e32 v69, v71
	v_add_f32_e32 v69, v69, v71
	v_fma_f32 v71, -v70, v72, 1.0
	v_fmac_f32_e32 v72, v71, v72
	v_div_scale_f32 v71, vcc, 1.0, v68, 1.0
	v_mul_f32_e32 v73, v71, v72
	v_fma_f32 v74, -v70, v73, v71
	v_fmac_f32_e32 v73, v74, v72
	v_fma_f32 v70, -v70, v73, v71
	v_div_scale_f32 v71, s[0:1], v69, v69, s28
	v_rcp_f32_e32 v74, v71
	v_div_fmas_f32 v70, v70, v72, v73
	v_div_fixup_f32 v76, v70, v68, 1.0
	s_movk_i32 s0, 0x3000
	v_fma_f32 v68, -v71, v74, 1.0
	v_fmac_f32_e32 v74, v68, v74
	v_div_scale_f32 v68, vcc, s28, v69, s28
	v_mul_f32_e32 v70, v68, v74
	v_fma_f32 v72, -v71, v70, v68
	v_fmac_f32_e32 v70, v72, v74
	v_fma_f32 v68, -v71, v70, v68
	v_lshl_add_u64 v[72:73], v[126:127], 0, v[80:81]
	v_div_fmas_f32 v68, v68, v74, v70
	v_lshl_add_u64 v[70:71], v[72:73], 0, s[92:93]
	v_add_co_u32_e32 v72, vcc, s0, v72
	v_div_fixup_f32 v78, v68, v69, s28
	v_lshlrev_b64 v[68:69], 12, v[124:125]
	v_addc_co_u32_e32 v73, vcc, 0, v73, vcc
	v_lshl_add_u64 v[82:83], s[88:89], 0, v[68:69]
	v_lshl_add_u64 v[68:69], v[128:129], 2, s[84:85]
	global_load_dwordx2 v[116:117], v[70:71], off
	global_load_dwordx4 v[84:87], v[68:69], off
	global_load_dwordx2 v[118:119], v[70:71], off offset:32
	global_load_dwordx4 v[88:91], v[68:69], off offset:64
	global_load_dwordx2 v[120:121], v[70:71], off offset:64
	global_load_dwordx4 v[92:95], v[68:69], off offset:128
	global_load_dwordx2 v[122:123], v[70:71], off offset:96
	global_load_dwordx4 v[96:99], v[68:69], off offset:192
	global_load_dwordx2 v[132:133], v[70:71], off offset:128
	global_load_dwordx4 v[100:103], v[68:69], off offset:256
	global_load_dwordx2 v[134:135], v[70:71], off offset:160
	global_load_dwordx4 v[104:107], v[68:69], off offset:320
	global_load_dwordx2 v[136:137], v[70:71], off offset:192
	global_load_dwordx4 v[108:111], v[68:69], off offset:384
	global_load_dwordx2 v[138:139], v[70:71], off offset:224
	global_load_dwordx4 v[112:115], v[68:69], off offset:448
	v_pk_mul_f32 v[56:57], v[56:57], v[78:79] op_sel_hi:[1,0]
	v_pk_mul_f32 v[58:59], v[58:59], v[78:79] op_sel_hi:[1,0]
	v_pk_fma_f32 v[56:57], v[64:65], v[76:77], v[56:57] op_sel_hi:[1,0,1] neg_lo:[0,0,1] neg_hi:[0,0,1]
	v_pk_fma_f32 v[58:59], v[66:67], v[76:77], v[58:59] op_sel_hi:[1,0,1] neg_lo:[0,0,1] neg_hi:[0,0,1]
	v_pk_mul_f32 v[64:65], v[56:57], v[56:57]
	v_pk_mul_f32 v[66:67], v[58:59], v[58:59]
	v_pk_mul_f32 v[52:53], v[52:53], v[78:79] op_sel_hi:[1,0]
	v_add_f32_e32 v64, v64, v65
	v_pk_fma_f32 v[52:53], v[60:61], v[76:77], v[52:53] op_sel_hi:[1,0,1] neg_lo:[0,0,1] neg_hi:[0,0,1]
	v_add_f32_e32 v64, v66, v64
	v_pk_mul_f32 v[54:55], v[54:55], v[78:79] op_sel_hi:[1,0]
	v_pk_mul_f32 v[60:61], v[52:53], v[52:53]
	v_add_f32_e32 v64, v67, v64
	v_pk_fma_f32 v[54:55], v[62:63], v[76:77], v[54:55] op_sel_hi:[1,0,1] neg_lo:[0,0,1] neg_hi:[0,0,1]
	v_add_f32_e32 v60, v60, v64
	v_pk_mul_f32 v[62:63], v[54:55], v[54:55]
	v_pk_mul_f32 v[44:45], v[44:45], v[78:79] op_sel_hi:[1,0]
	v_add_f32_e32 v60, v61, v60
	v_pk_fma_f32 v[44:45], v[48:49], v[76:77], v[44:45] op_sel_hi:[1,0,1] neg_lo:[0,0,1] neg_hi:[0,0,1]
	v_add_f32_e32 v60, v62, v60
	v_pk_mul_f32 v[46:47], v[46:47], v[78:79] op_sel_hi:[1,0]
	v_pk_mul_f32 v[48:49], v[44:45], v[44:45]
	v_add_f32_e32 v60, v63, v60
	v_pk_fma_f32 v[46:47], v[50:51], v[76:77], v[46:47] op_sel_hi:[1,0,1] neg_lo:[0,0,1] neg_hi:[0,0,1]
	v_add_f32_e32 v48, v48, v60
	v_pk_mul_f32 v[50:51], v[46:47], v[46:47]
	v_pk_mul_f32 v[36:37], v[36:37], v[78:79] op_sel_hi:[1,0]
	v_add_f32_e32 v48, v49, v48
	v_pk_fma_f32 v[36:37], v[40:41], v[76:77], v[36:37] op_sel_hi:[1,0,1] neg_lo:[0,0,1] neg_hi:[0,0,1]
	v_add_f32_e32 v48, v50, v48
	v_pk_mul_f32 v[38:39], v[38:39], v[78:79] op_sel_hi:[1,0]
	v_pk_mul_f32 v[40:41], v[36:37], v[36:37]
	v_add_f32_e32 v48, v51, v48
	v_pk_fma_f32 v[38:39], v[42:43], v[76:77], v[38:39] op_sel_hi:[1,0,1] neg_lo:[0,0,1] neg_hi:[0,0,1]
	v_add_f32_e32 v40, v40, v48
	v_pk_mul_f32 v[42:43], v[38:39], v[38:39]
	v_pk_mul_f32 v[28:29], v[28:29], v[78:79] op_sel_hi:[1,0]
	v_add_f32_e32 v40, v41, v40
	v_pk_fma_f32 v[28:29], v[32:33], v[76:77], v[28:29] op_sel_hi:[1,0,1] neg_lo:[0,0,1] neg_hi:[0,0,1]
	v_add_f32_e32 v40, v42, v40
	v_pk_mul_f32 v[30:31], v[30:31], v[78:79] op_sel_hi:[1,0]
	v_pk_mul_f32 v[32:33], v[28:29], v[28:29]
	v_add_f32_e32 v40, v43, v40
	v_pk_fma_f32 v[30:31], v[34:35], v[76:77], v[30:31] op_sel_hi:[1,0,1] neg_lo:[0,0,1] neg_hi:[0,0,1]
	v_add_f32_e32 v32, v32, v40
	v_pk_mul_f32 v[34:35], v[30:31], v[30:31]
	v_pk_mul_f32 v[20:21], v[20:21], v[78:79] op_sel_hi:[1,0]
	v_add_f32_e32 v32, v33, v32
	v_pk_fma_f32 v[20:21], v[24:25], v[76:77], v[20:21] op_sel_hi:[1,0,1] neg_lo:[0,0,1] neg_hi:[0,0,1]
	v_add_f32_e32 v32, v34, v32
	v_pk_mul_f32 v[22:23], v[22:23], v[78:79] op_sel_hi:[1,0]
	v_pk_mul_f32 v[24:25], v[20:21], v[20:21]
	v_add_f32_e32 v32, v35, v32
	v_pk_fma_f32 v[22:23], v[26:27], v[76:77], v[22:23] op_sel_hi:[1,0,1] neg_lo:[0,0,1] neg_hi:[0,0,1]
	v_add_f32_e32 v24, v24, v32
	v_pk_mul_f32 v[26:27], v[22:23], v[22:23]
	v_pk_mul_f32 v[12:13], v[12:13], v[78:79] op_sel_hi:[1,0]
	v_add_f32_e32 v24, v25, v24
	v_pk_fma_f32 v[12:13], v[16:17], v[76:77], v[12:13] op_sel_hi:[1,0,1] neg_lo:[0,0,1] neg_hi:[0,0,1]
	v_add_f32_e32 v24, v26, v24
	v_pk_mul_f32 v[14:15], v[14:15], v[78:79] op_sel_hi:[1,0]
	v_pk_mul_f32 v[16:17], v[12:13], v[12:13]
	v_add_f32_e32 v24, v27, v24
	v_pk_fma_f32 v[14:15], v[18:19], v[76:77], v[14:15] op_sel_hi:[1,0,1] neg_lo:[0,0,1] neg_hi:[0,0,1]
	v_add_f32_e32 v16, v16, v24
	v_pk_mul_f32 v[18:19], v[14:15], v[14:15]
	v_pk_mul_f32 v[4:5], v[4:5], v[78:79] op_sel_hi:[1,0]
	v_add_f32_e32 v16, v17, v16
	v_pk_fma_f32 v[8:9], v[8:9], v[76:77], v[4:5] op_sel_hi:[1,0,1] neg_lo:[0,0,1] neg_hi:[0,0,1]
	v_add_f32_e32 v16, v18, v16
	v_pk_mul_f32 v[6:7], v[6:7], v[78:79] op_sel_hi:[1,0]
	v_pk_mul_f32 v[4:5], v[8:9], v[8:9]
	v_add_f32_e32 v16, v19, v16
	v_pk_fma_f32 v[10:11], v[10:11], v[76:77], v[6:7] op_sel_hi:[1,0,1] neg_lo:[0,0,1] neg_hi:[0,0,1]
	v_add_f32_e32 v4, v4, v16
	v_pk_mul_f32 v[6:7], v[10:11], v[10:11]
	v_add_f32_e32 v4, v5, v4
	v_add_f32_e32 v4, v6, v4
	v_add_f32_e32 v6, v7, v4
	ds_swizzle_b32 v7, v6 offset:swizzle(SWAP,16)
	v_mov_b32_e32 v18, 0x358637bd
	s_mov_b32 s87, s27
	v_lshl_add_u64 v[4:5], v[82:83], 0, s[86:87]
	v_lshl_add_u64 v[16:17], v[4:5], 0, v[80:81]
	s_waitcnt lgkmcnt(0)
; __device__ __forceinline__ unsigned cvtpk(float lo, float hi) { f32x2 v = {lo, hi}; bf16x2_t b = __builtin_convertvector(v, bf16x2_t); return __builtin_bit_cast(unsigned, b); }
; __device__ __forceinline__ float bflo(unsigned u) { return __uint_as_float(u << 16); }
; __device__ __forceinline__ float bfhi(unsigned u) { return __uint_as_float(u & 0xffff0000u); }
; template <bool DIFF>
; __device__ __forceinline__ void attn_item(LAS unsigned char* lds, const bf16_t* Z, bf16_t* MIX, int b, int h, int t, float lam, float shift, const float* gain, int tid, int wid, int lane) {
;     ...
;     ss = quad_sum(ss);
;     const float r = rsqrtf(ss * (1.0f / 128.0f) + EPS) * (DIFF ? 0.8f : 1.0f);
;     const int row = row0 + q16;
;     const bf16_t* gp = Z + (size_t)row * DIN + gcol + 4 * quad;
;     bf16_t* op = MIX + (size_t)row * DM + (DIFF ? 1024 : 0) + 128 * h + 4 * quad;
; #pragma unroll
;     for (int eb = 0; eb < 8; ++eb) {
;         const u32x2 gw = *(const u32x2*)(gp + 16 * eb);
;         const f32x4 gn = *(const f32x4*)(gain + 16 * eb + 4 * quad);
;         u32x2 w; w.x = cvtpk(O[0][eb][0] * r * gn.x * bflo(gw.x), O[0][eb][1] * r * gn.y * bfhi(gw.x));
;         w.y = cvtpk(O[0][eb][2] * r * gn.z * bflo(gw.y), O[0][eb][3] * r * gn.w * bfhi(gw.y));
;         *(u32x2*)(op + 16 * eb) = w;
	v_add_f32_e32 v6, v6, v7
	v_mov_b32_e32 v7, v6
	s_nop 1
	v_permlane32_swap_b32_e32 v6, v7
	v_add_f32_e32 v6, v6, v7
	v_fmamk_f32 v6, v6, 0x3c000000, v18
	v_mul_f32_e32 v7, 0x4b800000, v6
	v_cmp_gt_f32_e32 vcc, s42, v6
	s_nop 1
	v_cndmask_b32_e32 v6, v6, v7, vcc
	v_rsq_f32_e32 v24, v6
	s_nop 0
	v_mul_f32_e32 v25, 0x45800000, v24
	v_cndmask_b32_e32 v24, v24, v25, vcc
	v_mul_f32_e32 v24, 0x3f4ccccd, v24
	s_waitcnt vmcnt(0)
	v_mbcnt_lo_u32_b32 v150, -1, 0
	v_mbcnt_hi_u32_b32 v150, -1, v150
	v_and_b32_e32 v150, 16, v150
	v_lshrrev_b32_e32 v151, 1, v150
	v_add_u32_e32 v150, v150, v151
	v_mov_b32_e32 v151, 0
	v_lshl_add_u64 v[148:149], v[16:17], 0, v[150:151]
	v_pk_mul_f32 v[56:57], v[56:57], v[24:25] op_sel_hi:[1,0]
	v_pk_mul_f32 v[58:59], v[58:59], v[24:25] op_sel_hi:[1,0]
	v_lshlrev_b32_e32 v60, 16, v116
	v_and_b32_e32 v61, 0xffff0000, v116
	v_lshlrev_b32_e32 v62, 16, v117
	v_and_b32_e32 v63, 0xffff0000, v117
	v_pk_mul_f32 v[56:57], v[84:85], v[56:57]
	v_pk_mul_f32 v[58:59], v[86:87], v[58:59]
	v_pk_mul_f32 v[56:57], v[56:57], v[60:61]
	v_pk_mul_f32 v[58:59], v[58:59], v[62:63]
	v_cvt_pk_bf16_f32 v56, v56, v57
	v_cvt_pk_bf16_f32 v57, v58, v59
	v_pk_mul_f32 v[52:53], v[52:53], v[24:25] op_sel_hi:[1,0]
	v_pk_mul_f32 v[54:55], v[54:55], v[24:25] op_sel_hi:[1,0]
	v_lshlrev_b32_e32 v40, 16, v118
	v_and_b32_e32 v41, 0xffff0000, v118
	v_lshlrev_b32_e32 v42, 16, v119
	v_and_b32_e32 v43, 0xffff0000, v119
	v_pk_mul_f32 v[52:53], v[88:89], v[52:53]
	v_pk_mul_f32 v[54:55], v[90:91], v[54:55]
	v_pk_mul_f32 v[52:53], v[52:53], v[40:41]
	v_pk_mul_f32 v[54:55], v[54:55], v[42:43]
	v_cvt_pk_bf16_f32 v58, v52, v53
	v_cvt_pk_bf16_f32 v59, v54, v55
	s_nop 1
	v_permlane16_swap_b32_e32 v56, v58
	v_permlane16_swap_b32_e32 v57, v59
	global_store_dwordx4 v[148:149], v[56:59], off offset:2048
	v_pk_mul_f32 v[44:45], v[44:45], v[24:25] op_sel_hi:[1,0]
	v_pk_mul_f32 v[46:47], v[46:47], v[24:25] op_sel_hi:[1,0]
	v_lshlrev_b32_e32 v60, 16, v120
	v_and_b32_e32 v61, 0xffff0000, v120
	v_lshlrev_b32_e32 v62, 16, v121
	v_and_b32_e32 v63, 0xffff0000, v121
	v_pk_mul_f32 v[44:45], v[92:93], v[44:45]
	v_pk_mul_f32 v[46:47], v[94:95], v[46:47]
	v_pk_mul_f32 v[44:45], v[44:45], v[60:61]
	v_pk_mul_f32 v[46:47], v[46:47], v[62:63]
	v_cvt_pk_bf16_f32 v44, v44, v45
	v_cvt_pk_bf16_f32 v45, v46, v47
	v_pk_mul_f32 v[36:37], v[36:37], v[24:25] op_sel_hi:[1,0]
	v_pk_mul_f32 v[38:39], v[38:39], v[24:25] op_sel_hi:[1,0]
	v_lshlrev_b32_e32 v40, 16, v122
	v_and_b32_e32 v41, 0xffff0000, v122
	v_lshlrev_b32_e32 v42, 16, v123
	v_and_b32_e32 v43, 0xffff0000, v123
	v_pk_mul_f32 v[36:37], v[96:97], v[36:37]
	v_pk_mul_f32 v[38:39], v[98:99], v[38:39]
	v_pk_mul_f32 v[36:37], v[36:37], v[40:41]
	v_pk_mul_f32 v[38:39], v[38:39], v[42:43]
	v_cvt_pk_bf16_f32 v46, v36, v37
	v_cvt_pk_bf16_f32 v47, v38, v39
	s_nop 1
	v_permlane16_swap_b32_e32 v44, v46
	v_permlane16_swap_b32_e32 v45, v47
	global_store_dwordx4 v[148:149], v[44:47], off offset:2112
	v_pk_mul_f32 v[28:29], v[28:29], v[24:25] op_sel_hi:[1,0]
	v_pk_mul_f32 v[30:31], v[30:31], v[24:25] op_sel_hi:[1,0]
	v_lshlrev_b32_e32 v60, 16, v132
	v_and_b32_e32 v61, 0xffff0000, v132
	v_lshlrev_b32_e32 v62, 16, v133
	v_and_b32_e32 v63, 0xffff0000, v133
	v_pk_mul_f32 v[28:29], v[100:101], v[28:29]
	v_pk_mul_f32 v[30:31], v[102:103], v[30:31]
	v_pk_mul_f32 v[28:29], v[28:29], v[60:61]
	v_pk_mul_f32 v[30:31], v[30:31], v[62:63]
	v_cvt_pk_bf16_f32 v28, v28, v29
	v_cvt_pk_bf16_f32 v29, v30, v31
	v_pk_mul_f32 v[20:21], v[20:21], v[24:25] op_sel_hi:[1,0]
	v_pk_mul_f32 v[22:23], v[22:23], v[24:25] op_sel_hi:[1,0]
	v_lshlrev_b32_e32 v40, 16, v134
	v_and_b32_e32 v41, 0xffff0000, v134
	v_lshlrev_b32_e32 v42, 16, v135
	v_and_b32_e32 v43, 0xffff0000, v135
	v_pk_mul_f32 v[20:21], v[104:105], v[20:21]
	v_pk_mul_f32 v[22:23], v[106:107], v[22:23]
	v_pk_mul_f32 v[20:21], v[20:21], v[40:41]
	v_pk_mul_f32 v[22:23], v[22:23], v[42:43]
	v_cvt_pk_bf16_f32 v30, v20, v21
	v_cvt_pk_bf16_f32 v31, v22, v23
	s_nop 1
	v_permlane16_swap_b32_e32 v28, v30
	v_permlane16_swap_b32_e32 v29, v31
	global_store_dwordx4 v[148:149], v[28:31], off offset:2176
	v_pk_mul_f32 v[12:13], v[12:13], v[24:25] op_sel_hi:[1,0]
	v_pk_mul_f32 v[14:15], v[14:15], v[24:25] op_sel_hi:[1,0]
	v_lshlrev_b32_e32 v60, 16, v136
	v_and_b32_e32 v61, 0xffff0000, v136
	v_lshlrev_b32_e32 v62, 16, v137
	v_and_b32_e32 v63, 0xffff0000, v137
	v_pk_mul_f32 v[12:13], v[108:109], v[12:13]
	v_pk_mul_f32 v[14:15], v[110:111], v[14:15]
	v_pk_mul_f32 v[12:13], v[12:13], v[60:61]
	v_pk_mul_f32 v[14:15], v[14:15], v[62:63]
	v_cvt_pk_bf16_f32 v12, v12, v13
	v_cvt_pk_bf16_f32 v13, v14, v15
	v_pk_mul_f32 v[8:9], v[8:9], v[24:25] op_sel_hi:[1,0]
	v_pk_mul_f32 v[10:11], v[10:11], v[24:25] op_sel_hi:[1,0]
	v_lshlrev_b32_e32 v40, 16, v138
	v_and_b32_e32 v41, 0xffff0000, v138
	v_lshlrev_b32_e32 v42, 16, v139
	v_and_b32_e32 v43, 0xffff0000, v139
	v_pk_mul_f32 v[8:9], v[112:113], v[8:9]
	v_pk_mul_f32 v[10:11], v[114:115], v[10:11]
	v_pk_mul_f32 v[8:9], v[8:9], v[40:41]
	v_pk_mul_f32 v[10:11], v[10:11], v[42:43]
	v_cvt_pk_bf16_f32 v14, v8, v9
	v_cvt_pk_bf16_f32 v15, v10, v11
	s_nop 1
	v_permlane16_swap_b32_e32 v12, v14
	v_permlane16_swap_b32_e32 v13, v15
	global_store_dwordx4 v[148:149], v[12:15], off offset:2240
	s_nop 1
	v_mov_b32_e32 v15, v183
	s_cmp_lg_u32 s98, 0
	s_cbranch_scc1 .Lp2_item_done
	s_cmp_lt_i32 s9, 3
	s_cbranch_scc1 .LBB0_579
	s_cmp_lt_i32 s9, 4
	s_cbranch_scc1 .LBB0_580
	s_cmp_lt_i32 s9, 5
	s_cbranch_scc1 .LBB0_581
	s_cmp_lg_u32 s9, 5
	s_cbranch_scc0 .LBB0_582
	s_cmp_eq_u32 s9, 6
	s_cselect_b64 vcc, -1, 0
	v_mov_b32_e32 v4, 0xba38b001
	v_mov_b32_e32 v5, 0xbab8b5c7
	v_cndmask_b32_e32 v12, v4, v5, vcc
	s_cbranch_execz .LBB0_583
	s_branch .LBB0_584
